# hand-scheduled SwiGLU epilogue for the gate-up GEMM with per-row rstd cached across tiles of a row panel
# speedup vs baseline: 1.0162x; 1.0162x over previous
; #define PG8_STAGE(bufoff, gbase, voff) do { _Pragma("unroll") for (int _i = 0; _i < 2; ++_i) { \
;         const unsigned _m0 = ldsb + (unsigned)((bufoff) + _i * 8192); const char* _gb = (const char*)(gbase); \
;         asm volatile("s_mov_b32 m0, %0\n\ts_nop 0\n\tglobal_load_lds_dwordx4 %1, %2" :: "s"(_m0), "v"((voff)[_i]), "s"(_gb) : "m0", "memory"); } } while (0)
; #define PG8_BAR __builtin_amdgcn_s_barrier()
; template <class Epi, bool ALIGN_EPI>
; __device__ __forceinline__ void gemm_phase(LAS unsigned char* lds, const Gemm g, const StaticOrder& S, const Epi& E) {
;     ...
;     unsigned voffA[2], voffB[2];
; #pragma unroll
;     for (int i = 0; i < 2; ++i) { int R, C; stage_rc(tid * 16 + i * 8192, R, C); const int Rb = (R & ~31) + perm32(R & 31);
;         voffA[i] = (unsigned)(R * lda + C) * 2u; voffB[i] = (unsigned)(Rb * K + C) * 2u; }
;     const size_t kstep = (size_t)(BK * 2);
;     const size_t hstepA = (size_t)HALF * lda * 2, hstepB = (size_t)HALF * K * 2;
;     const size_t tstepA = 2 * hstepA, tstepB = 2 * hstepB;
;     const unsigned ldsw = (unsigned)wid * 1024u;
;     const unsigned ldsb = (unsigned)(unsigned long)lds + ldsw;
;     const int aoff = lds_byte(wr * 64 + fr, fq * 8), boff = lds_byte(wc * 32 + fr, fq * 8);
;     ...
;     const char* cA = (const char*)g.A + (size_t)cur.pm * tstepA + (size_t)cur.pn * g.a_pn_off * 2 + (size_t)(cur.pm >> 4) * g.a_adj; const char* cB = (const char*)g.Bt + (size_t)cur.pn * tstepB;
;     PG8_STAGE(PG8_SB(0, 0), cB, voffB); PG8_STAGE(PG8_SB(0, 1), cB + hstepB, voffB); PG8_STAGE(PG8_SA(0, 0), cA, voffA); PG8_STAGE(PG8_SA(0, 1), cA + hstepA, voffA);
;     if (wr == 1) PG8_BAR;
.LBB0_297:
	s_andn2_b64 vcc, exec, s[26:27]
	s_cbranch_vccnz .LBB0_328
	s_mov_b32 s98, -1
	v_writelane_b32 v254, s85, 39
	v_writelane_b32 v254, s80, 40
	v_bfe_i32 v4, v2, 27, 1
	v_writelane_b32 v254, s67, 41
	v_lshlrev_b32_e32 v3, 4, v2
	v_lshrrev_b32_e32 v4, 22, v4
	v_writelane_b32 v254, s65, 42
	v_add_u32_e32 v4, v3, v4
	v_writelane_b32 v254, s53, 43
	v_and_b32_e32 v4, 0xfffffc00, v4
	v_writelane_b32 v254, s94, 31
	v_sub_u32_e32 v4, v3, v4
	v_ashrrev_i32_e32 v0, 31, v2
	v_writelane_b32 v254, s95, 32
	s_waitcnt lgkmcnt(0)
	v_lshrrev_b32_e32 v5, 4, v4
	v_writelane_b32 v254, s60, 33
	v_lshrrev_b32_e32 v0, 26, v0
	v_bitop3_b32 v4, v5, v4, 32 bitop3:0x6c
	v_writelane_b32 v254, s61, 34
	v_add_u32_e32 v0, v2, v0
	v_ashrrev_i32_e32 v6, 31, v4
	v_writelane_b32 v254, s58, 35
	v_ashrrev_i32_e32 v0, 6, v0
	v_lshrrev_b32_e32 v6, 26, v6
	v_writelane_b32 v254, s59, 36
	v_lshlrev_b32_e32 v5, 3, v0
	v_add_u32_e32 v6, v4, v6
	s_lshl_b64 s[8:9], s[8:9], 1
	v_readlane_b32 s1, v254, 29
	v_and_b32_e32 v5, -16, v5
	v_ashrrev_i32_e32 v7, 6, v6
	v_and_b32_e32 v6, 0xc0, v6
	s_add_u32 s1, s1, s8
	v_readlane_b32 s8, v254, 30
	v_add_u32_e32 v5, v7, v5
	v_sub_u32_e32 v4, v4, v6
	s_addc_u32 s14, s8, s9
	v_lshlrev_b32_e32 v0, 5, v0
	v_ashrrev_i16_sdwa v4, v223, sext(v4) dst_sel:DWORD dst_unused:UNUSED_PAD src0_sel:DWORD src1_sel:BYTE_0
	v_lshlrev_b32_e32 v6, 1, v5
	v_lshrrev_b32_e32 v8, 2, v5
	v_and_b32_e32 v7, 3, v7
	s_mov_b32 s9, 0x1fffe0
	v_and_b32_e32 v0, 32, v0
	v_bfe_i32 v4, v4, 0, 16
	v_and_b32_e32 v6, 24, v6
	v_and_b32_e32 v8, 4, v8
	v_and_or_b32 v7, v5, s9, v7
	v_or3_b32 v6, v7, v8, v6
	v_add_lshl_u32 v4, v0, v4, 1
	v_add_u32_e32 v3, 0x2000, v3
	v_lshl_add_u32 v0, v5, 11, v4
	v_lshl_add_u32 v180, v6, 11, v4
	v_ashrrev_i32_e32 v4, 31, v3
	v_lshrrev_b32_e32 v4, 22, v4
	v_add_u32_e32 v4, v3, v4
	v_ashrrev_i32_e32 v4, 10, v4
	v_mul_i32_i24_e32 v5, 0x400, v4
	v_sub_u32_e32 v3, v3, v5
	v_lshrrev_b32_e32 v5, 4, v3
	v_bitop3_b32 v3, v5, v3, 32 bitop3:0x6c
	v_ashrrev_i32_e32 v6, 31, v3
	v_lshrrev_b32_e32 v6, 26, v6
	v_lshlrev_b32_e32 v5, 3, v4
	v_add_u32_e32 v6, v3, v6
	v_and_b32_e32 v5, -16, v5
	v_ashrrev_i32_e32 v7, 6, v6
	v_add_u32_e32 v5, v7, v5
	v_and_b32_e32 v7, 3, v7
	v_and_or_b32 v7, v5, s9, v7
	s_ashr_i32 s9, s5, 6
	v_and_b32_e32 v6, 0xc0, v6
	s_lshl_b32 s15, s9, 10
	s_ashr_i32 s55, s54, 31
	s_ashr_i32 s49, s48, 31
	s_ashr_i32 s8, s5, 8
	v_sub_u32_e32 v3, v3, v6
	s_add_i32 s15, s15, 0
	s_lshl_b64 s[26:27], s[54:55], 19
	s_lshl_b64 s[30:31], s[48:49], 19
	v_lshlrev_b32_e32 v4, 5, v4
	v_ashrrev_i16_sdwa v3, v223, sext(v3) dst_sel:DWORD dst_unused:UNUSED_PAD src0_sel:DWORD src1_sel:BYTE_0
	v_lshlrev_b32_e32 v6, 1, v5
	v_lshrrev_b32_e32 v8, 2, v5
	s_add_u32 s56, s1, s30
	v_and_b32_e32 v4, 32, v4
	v_bfe_i32 v3, v3, 0, 16
	v_and_b32_e32 v6, 24, v6
	v_and_b32_e32 v8, 4, v8
	s_addc_u32 s57, s14, s31
	s_add_i32 s29, s15, 0x10000
	s_add_i32 s42, s15, 0x12000
	s_add_i32 s43, s15, 0x14000
	v_or3_b32 v6, v7, v8, v6
	v_add_lshl_u32 v3, v4, v3, 1
	s_mov_b32 m0, s29
	s_nop 0
	global_load_lds_dwordx4 v180, s[56:57]
	s_add_u32 s30, s56, 0x40000
	v_lshl_add_u32 v182, v6, 11, v3
	s_mov_b32 m0, s42
	s_nop 0
	global_load_lds_dwordx4 v182, s[56:57]
	s_addc_u32 s31, s57, 0
	s_add_i32 s44, s15, 0x16000
	s_mov_b32 m0, s43
	s_nop 0
	global_load_lds_dwordx4 v180, s[30:31]
	s_add_u32 s58, s18, s26
	s_mov_b32 m0, s44
	s_nop 0
	global_load_lds_dwordx4 v182, s[30:31]
	s_addc_u32 s59, s19, s27
	s_add_i32 s45, s15, 0x2000
	s_add_i32 s55, s15, 0x4000
	s_mov_b32 m0, s15
	s_nop 0
	global_load_lds_dwordx4 v0, s[58:59]
	s_add_u32 s26, s58, 0x40000
	v_lshl_add_u32 v181, v5, 11, v3
	s_mov_b32 m0, s45
	s_nop 0
	global_load_lds_dwordx4 v181, s[58:59]
	s_addc_u32 s27, s59, 0
	s_add_i32 s88, s15, 0x6000
	s_mov_b32 m0, s55
	s_nop 0
	global_load_lds_dwordx4 v0, s[26:27]
	s_cmp_eq_u32 s8, 1
	s_mov_b32 m0, s88
	s_nop 0
	global_load_lds_dwordx4 v181, s[26:27]
	s_cselect_b64 s[26:27], -1, 0
	v_writelane_b32 v254, s26, 44
	s_mov_b32 s80, s68
	s_cmp_lg_u32 s8, 1
	v_writelane_b32 v254, s27, 45
	s_cbranch_scc1 .LBB0_300
	s_barrier

; __device__ __forceinline__ float silu_f(float g) { return g * __builtin_amdgcn_rcpf(1.0f + __builtin_amdgcn_exp2f(g * -1.4426950408889634f)); }
; __device__ __forceinline__ void rstd8(const float* ss, int row0, float (&rs)[2][4]) {
;     f32x4 p[2][4];
; #pragma unroll
;     for (int ai = 0; ai < 2; ++ai)
; #pragma unroll
;         for (int m = 0; m < 4; ++m) p[ai][m] = *(const f32x4*)(ss + 4 * (size_t)(row0 + ai * HALF + m * 16));
; #pragma unroll
;     for (int ai = 0; ai < 2; ++ai)
; #pragma unroll
;         for (int m = 0; m < 4; ++m) rs[ai][m] = __builtin_amdgcn_rsqf(((p[ai][m].x + p[ai][m].y) + (p[ai][m].z + p[ai][m].w)) * (1.0f / D) + EPS);
;     __device__ __forceinline__ void operator()(const f32x4 (&acc)[2][2][4][2], const Unit& u, int wr, int wc, int fr, int fq) const {
;         const int row0 = u.pm * BM + wr * 64 + fr, col0 = u.pn * HALF + wc * 32 + 8 * fq;
;         float rsv[2][4]; rstd8(ss, row0, rsv);
; #pragma unroll
;         for (int ai = 0; ai < 2; ++ai)
; #pragma unroll
;             for (int m = 0; m < 4; ++m) { const int row = row0 + ai * HALF + m * 16; const float rs = rsv[ai][m];
;                 f32x4 g0 = acc[ai][0][m][0] * rs, g1 = acc[ai][0][m][1] * rs; const f32x4 t0 = acc[ai][1][m][0] * rs, t1 = acc[ai][1][m][1] * rs;
;                 if (silu) {
; #pragma unroll
;                     for (int j = 0; j < 4; ++j) { g0[j] = silu_f(g0[j]); g1[j] = silu_f(g1[j]); } }
.LBB0_309:
	s_and_b64 vcc, exec, s[6:7]
	s_cbranch_vccz .Lep_fast
	s_lshl_b32 s4, s54, 8
	s_add_i32 s4, s4, s89
	v_or_b32_e32 v172, s4, v183
	v_ashrrev_i32_e32 v173, 31, v172
	v_or_b32_e32 v170, 16, v172
	v_lshl_add_u64 v[74:75], v[172:173], 4, s[24:25]
	v_ashrrev_i32_e32 v171, 31, v170
	v_lshl_add_u64 v[76:77], v[170:171], 4, s[24:25]
	flat_load_dwordx4 v[174:177], v[74:75]
	flat_load_dwordx4 v[154:157], v[76:77]
	v_or_b32_e32 v168, 32, v172
	v_or_b32_e32 v166, 48, v172
	v_ashrrev_i32_e32 v169, 31, v168
	v_ashrrev_i32_e32 v167, 31, v166
	v_add_u32_e32 v164, 0x80, v172
	v_add_u32_e32 v162, 0x90, v172
	v_lshl_add_u64 v[74:75], v[168:169], 4, s[24:25]
	v_lshl_add_u64 v[76:77], v[166:167], 4, s[24:25]
	v_ashrrev_i32_e32 v165, 31, v164
	v_ashrrev_i32_e32 v163, 31, v162
	v_add_u32_e32 v160, 0xa0, v172
	v_add_u32_e32 v158, 0xb0, v172
	flat_load_dwordx4 v[150:153], v[74:75]
	flat_load_dwordx4 v[146:149], v[76:77]
	v_lshl_add_u64 v[74:75], v[164:165], 4, s[24:25]
	v_lshl_add_u64 v[76:77], v[162:163], 4, s[24:25]
	v_ashrrev_i32_e32 v161, 31, v160
	v_ashrrev_i32_e32 v159, 31, v158
	flat_load_dwordx4 v[134:137], v[74:75]
	flat_load_dwordx4 v[114:117], v[76:77]
	v_lshl_add_u64 v[74:75], v[160:161], 4, s[24:25]
	v_lshl_add_u64 v[76:77], v[158:159], 4, s[24:25]
	flat_load_dwordx4 v[94:97], v[74:75]
	s_nop 0
	flat_load_dwordx4 v[74:77], v[76:77]
	s_and_b64 vcc, exec, s[6:7]
	s_waitcnt vmcnt(0) lgkmcnt(0)
	v_mov_b32_e32 v178, v175
	v_mov_b32_e32 v179, v176
	v_mov_b32_e32 v175, v177
	v_pk_add_f32 v[174:175], v[178:179], v[174:175]
	s_nop 0
	v_add_f32_e32 v159, v174, v175
	v_fmamk_f32 v159, v159, 0x3a800000, v224
	v_rsq_f32_e32 v174, v159
	s_nop 0
	v_pk_mul_f32 v[176:177], v[144:145], v[174:175] op_sel_hi:[1,0]
	v_pk_mul_f32 v[178:179], v[142:143], v[174:175] op_sel_hi:[1,0]
	v_pk_mul_f32 v[142:143], v[140:141], v[174:175] op_sel_hi:[1,0]
	v_pk_mul_f32 v[144:145], v[138:139], v[174:175] op_sel_hi:[1,0]
	s_cbranch_vccnz .LBB0_311
	v_mul_f32_e32 v139, 0xbfb8aa3b, v144
	v_exp_f32_e32 v139, v139
	v_mul_f32_e32 v159, 0xbfb8aa3b, v176
	v_exp_f32_e32 v159, v159
	v_mul_f32_e32 v138, 0xbfb8aa3b, v178
	v_add_f32_e32 v139, 1.0, v139
	v_rcp_f32_e32 v140, v139
	v_mul_f32_e32 v139, 0xbfb8aa3b, v179
	v_exp_f32_e32 v138, v138
	v_exp_f32_e32 v139, v139
	v_add_f32_e32 v159, 1.0, v159
	v_rcp_f32_e32 v188, v159
	v_mul_f32_e32 v159, 0xbfb8aa3b, v142
	v_add_f32_e32 v138, 1.0, v138
	v_add_f32_e32 v139, 1.0, v139
	v_exp_f32_e32 v159, v159
	v_rcp_f32_e32 v138, v138
	v_rcp_f32_e32 v139, v139
	v_mul_f32_e32 v141, 0xbfb8aa3b, v145
	v_add_f32_e32 v159, 1.0, v159
	v_rcp_f32_e32 v190, v159
	v_mul_f32_e32 v159, 0xbfb8aa3b, v177
	v_pk_mul_f32 v[178:179], v[178:179], v[138:139]
	v_mul_f32_e32 v138, 0xbfb8aa3b, v143
	v_exp_f32_e32 v141, v141
	v_exp_f32_e32 v159, v159
	v_exp_f32_e32 v138, v138
	v_add_f32_e32 v141, 1.0, v141
	v_add_f32_e32 v159, 1.0, v159
	v_add_f32_e32 v138, 1.0, v138
	v_rcp_f32_e32 v141, v141
	v_rcp_f32_e32 v189, v159
	v_rcp_f32_e32 v191, v138
	v_pk_mul_f32 v[144:145], v[144:145], v[140:141]
	v_pk_mul_f32 v[176:177], v[176:177], v[188:189]
	v_pk_mul_f32 v[142:143], v[142:143], v[190:191]

; __device__ __forceinline__ unsigned cvt_pk_bf16(float lo, float hi) { unsigned r; asm volatile("v_cvt_pk_bf16_f32 %0, %1, %2" : "=v"(r) : "v"(lo), "v"(hi)); return r; }
; __device__ __forceinline__ float silu_f(float g) { return g * __builtin_amdgcn_rcpf(1.0f + __builtin_amdgcn_exp2f(g * -1.4426950408889634f)); }
; __device__ __forceinline__ void rstd8(const float* ss, int row0, float (&rs)[2][4]) {
;     f32x4 p[2][4];
; #pragma unroll
;     for (int ai = 0; ai < 2; ++ai)
; #pragma unroll
;         for (int m = 0; m < 4; ++m) p[ai][m] = *(const f32x4*)(ss + 4 * (size_t)(row0 + ai * HALF + m * 16));
; #pragma unroll
;     for (int ai = 0; ai < 2; ++ai)
; #pragma unroll
;         for (int m = 0; m < 4; ++m) rs[ai][m] = __builtin_amdgcn_rsqf(((p[ai][m].x + p[ai][m].y) + (p[ai][m].z + p[ai][m].w)) * (1.0f / D) + EPS);
;     __device__ __forceinline__ void operator()(const f32x4 (&acc)[2][2][4][2], const Unit& u, int wr, int wc, int fr, int fq) const {
;         const int row0 = u.pm * BM + wr * 64 + fr, col0 = u.pn * HALF + wc * 32 + 8 * fq;
;         float rsv[2][4]; rstd8(ss, row0, rsv);
; #pragma unroll
;         for (int ai = 0; ai < 2; ++ai)
; #pragma unroll
;             for (int m = 0; m < 4; ++m) { const int row = row0 + ai * HALF + m * 16; const float rs = rsv[ai][m];
;                 f32x4 g0 = acc[ai][0][m][0] * rs, g1 = acc[ai][0][m][1] * rs; const f32x4 t0 = acc[ai][1][m][0] * rs, t1 = acc[ai][1][m][1] * rs;
;                 if (silu) {
; #pragma unroll
;                     for (int j = 0; j < 4; ++j) { g0[j] = silu_f(g0[j]); g1[j] = silu_f(g1[j]); } }
;                 g0 = g0 * t0; g1 = g1 * t1;
;                 u32x4 w; w.x = cvt_pk_bf16(g0[0], g0[1]); w.y = cvt_pk_bf16(g0[2], g0[3]); w.z = cvt_pk_bf16(g1[0], g1[1]); w.w = cvt_pk_bf16(g1[2], g1[3]);
;                 *(u32x4*)(O + (size_t)row * ldc + col0 + (size_t)(row >> 12) * adj) = w; }
.Lep_join:
	s_cbranch_vccnz .LBB0_302
	v_readlane_b32 s4, v254, 44
	v_readlane_b32 s5, v254, 45
	s_andn2_b64 vcc, exec, s[4:5]
	s_cbranch_vccnz .LBB0_301
	s_barrier
	s_branch .LBB0_301
.Lep_fast:
	s_lshl_b32 s4, s54, 8
	s_add_i32 s4, s4, s89
	v_or_b32_e32 v178, s4, v183
	s_lshl_b32 s5, s0, 1
	v_lshl_or_b32 v179, s48, 7, v184
	s_lshl_b32 s30, s5, 4
	s_mul_i32 s31, s5, 80
	v_mul_lo_u32 v190, v178, s5
	v_mov_b32_e32 v188, 1.0
	v_mov_b32_e32 v189, 1.0
	v_lshl_add_u32 v190, v179, 1, v190
	s_cmp_eq_u32 s54, s98
	s_cbranch_scc1 .Lep_have_rs
	v_lshlrev_b32_e32 v178, 4, v178
	global_load_dwordx4 v[146:149], v178, s[24:25]
	global_load_dwordx4 v[150:153], v178, s[24:25] offset:256
	global_load_dwordx4 v[154:157], v178, s[24:25] offset:512
	global_load_dwordx4 v[158:161], v178, s[24:25] offset:768
	global_load_dwordx4 v[162:165], v178, s[24:25] offset:2048
	global_load_dwordx4 v[166:169], v178, s[24:25] offset:2304
	global_load_dwordx4 v[170:173], v178, s[24:25] offset:2560
	global_load_dwordx4 v[174:177], v178, s[24:25] offset:2816
	s_mov_b32 s98, s54
	s_waitcnt vmcnt(0)
	v_add_f32_e32 v146, v146, v147
	v_add_f32_e32 v148, v148, v149
	v_add_f32_e32 v150, v150, v151
	v_add_f32_e32 v152, v152, v153
	v_add_f32_e32 v154, v154, v155
	v_add_f32_e32 v156, v156, v157
	v_add_f32_e32 v158, v158, v159
	v_add_f32_e32 v160, v160, v161
	v_add_f32_e32 v162, v162, v163
	v_add_f32_e32 v164, v164, v165
	v_add_f32_e32 v166, v166, v167
	v_add_f32_e32 v168, v168, v169
	v_add_f32_e32 v170, v170, v171
	v_add_f32_e32 v172, v172, v173
	v_add_f32_e32 v174, v174, v175
	v_add_f32_e32 v176, v176, v177
	v_add_f32_e32 v146, v146, v148
	v_add_f32_e32 v150, v150, v152
	v_add_f32_e32 v154, v154, v156
	v_add_f32_e32 v158, v158, v160
	v_add_f32_e32 v162, v162, v164
	v_add_f32_e32 v166, v166, v168
	v_add_f32_e32 v170, v170, v172
	v_add_f32_e32 v174, v174, v176
	v_fmamk_f32 v146, v146, 0x3a800000, v224
	v_fmamk_f32 v150, v150, 0x3a800000, v224
	v_fmamk_f32 v154, v154, 0x3a800000, v224
	v_fmamk_f32 v158, v158, 0x3a800000, v224
	v_fmamk_f32 v162, v162, 0x3a800000, v224
	v_fmamk_f32 v166, v166, 0x3a800000, v224
	v_fmamk_f32 v170, v170, 0x3a800000, v224
	v_fmamk_f32 v174, v174, 0x3a800000, v224
	v_rsq_f32_e32 v240, v146
	v_rsq_f32_e32 v241, v150
	v_rsq_f32_e32 v242, v154
	v_rsq_f32_e32 v243, v158
	v_rsq_f32_e32 v244, v162
	v_rsq_f32_e32 v245, v166
	v_rsq_f32_e32 v246, v170
	v_rsq_f32_e32 v247, v174
	s_nop 0
.Lep_have_rs:
	v_mul_f32_e32 v170, 0xbfb8aa3b, v240
	v_mul_f32_e32 v172, v240, v240
	v_pk_mul_f32 v[146:147], v[142:143], v[170:171] op_sel_hi:[1,0]
	v_pk_mul_f32 v[148:149], v[144:145], v[170:171] op_sel_hi:[1,0]
	v_pk_mul_f32 v[150:151], v[138:139], v[170:171] op_sel_hi:[1,0]
	v_pk_mul_f32 v[152:153], v[140:141], v[170:171] op_sel_hi:[1,0]
	v_exp_f32_e32 v146, v146
	v_exp_f32_e32 v147, v147
	v_exp_f32_e32 v148, v148
	v_exp_f32_e32 v149, v149
	v_exp_f32_e32 v150, v150
	v_exp_f32_e32 v151, v151
	v_exp_f32_e32 v152, v152
	v_exp_f32_e32 v153, v153
	v_pk_mul_f32 v[142:143], v[142:143], v[130:131]
	v_pk_mul_f32 v[144:145], v[144:145], v[132:133]
	v_pk_mul_f32 v[138:139], v[138:139], v[126:127]
	v_pk_mul_f32 v[140:141], v[140:141], v[128:129]
	v_pk_add_f32 v[146:147], v[146:147], v[188:189]
	v_pk_add_f32 v[148:149], v[148:149], v[188:189]
	v_pk_add_f32 v[150:151], v[150:151], v[188:189]
	v_pk_add_f32 v[152:153], v[152:153], v[188:189]
	v_pk_mul_f32 v[142:143], v[142:143], v[172:173] op_sel_hi:[1,0]
	v_pk_mul_f32 v[144:145], v[144:145], v[172:173] op_sel_hi:[1,0]
	v_pk_mul_f32 v[138:139], v[138:139], v[172:173] op_sel_hi:[1,0]
	v_pk_mul_f32 v[140:141], v[140:141], v[172:173] op_sel_hi:[1,0]
	v_rcp_f32_e32 v146, v146
	v_rcp_f32_e32 v147, v147
	v_rcp_f32_e32 v148, v148
	v_rcp_f32_e32 v149, v149
	v_rcp_f32_e32 v150, v150
	v_rcp_f32_e32 v151, v151
	v_rcp_f32_e32 v152, v152
	v_rcp_f32_e32 v153, v153
	v_mul_f32_e32 v174, 0xbfb8aa3b, v241
	v_mul_f32_e32 v176, v241, v241
	v_pk_mul_f32 v[154:155], v[122:123], v[174:175] op_sel_hi:[1,0]
	v_pk_mul_f32 v[156:157], v[124:125], v[174:175] op_sel_hi:[1,0]
	v_pk_mul_f32 v[158:159], v[118:119], v[174:175] op_sel_hi:[1,0]
	v_pk_mul_f32 v[160:161], v[120:121], v[174:175] op_sel_hi:[1,0]
	v_pk_mul_f32 v[142:143], v[142:143], v[146:147]
	v_pk_mul_f32 v[144:145], v[144:145], v[148:149]
	v_pk_mul_f32 v[138:139], v[138:139], v[150:151]
	v_pk_mul_f32 v[140:141], v[140:141], v[152:153]
	v_cvt_pk_bf16_f32 v162, v142, v143
	v_cvt_pk_bf16_f32 v163, v144, v145
	v_cvt_pk_bf16_f32 v164, v138, v139
	v_cvt_pk_bf16_f32 v165, v140, v141
	global_store_dwordx4 v190, v[162:165], s[10:11]
	v_add_u32_e32 v190, s30, v190
	v_exp_f32_e32 v154, v154
	v_exp_f32_e32 v155, v155
	v_exp_f32_e32 v156, v156
	v_exp_f32_e32 v157, v157
	v_exp_f32_e32 v158, v158
	v_exp_f32_e32 v159, v159
	v_exp_f32_e32 v160, v160
	v_exp_f32_e32 v161, v161
	v_pk_mul_f32 v[122:123], v[122:123], v[110:111]
	v_pk_mul_f32 v[124:125], v[124:125], v[112:113]
	v_pk_mul_f32 v[118:119], v[118:119], v[106:107]
	v_pk_mul_f32 v[120:121], v[120:121], v[108:109]
	v_pk_add_f32 v[154:155], v[154:155], v[188:189]
	v_pk_add_f32 v[156:157], v[156:157], v[188:189]
	v_pk_add_f32 v[158:159], v[158:159], v[188:189]
	v_pk_add_f32 v[160:161], v[160:161], v[188:189]
	v_pk_mul_f32 v[122:123], v[122:123], v[176:177] op_sel_hi:[1,0]
	v_pk_mul_f32 v[124:125], v[124:125], v[176:177] op_sel_hi:[1,0]
	v_pk_mul_f32 v[118:119], v[118:119], v[176:177] op_sel_hi:[1,0]
	v_pk_mul_f32 v[120:121], v[120:121], v[176:177] op_sel_hi:[1,0]
	v_rcp_f32_e32 v154, v154
	v_rcp_f32_e32 v155, v155
	v_rcp_f32_e32 v156, v156
	v_rcp_f32_e32 v157, v157
	v_rcp_f32_e32 v158, v158
	v_rcp_f32_e32 v159, v159
	v_rcp_f32_e32 v160, v160
	v_rcp_f32_e32 v161, v161
; __device__ __forceinline__ unsigned cvt_pk_bf16(float lo, float hi) { unsigned r; asm volatile("v_cvt_pk_bf16_f32 %0, %1, %2" : "=v"(r) : "v"(lo), "v"(hi)); return r; }
; __device__ __forceinline__ float silu_f(float g) { return g * __builtin_amdgcn_rcpf(1.0f + __builtin_amdgcn_exp2f(g * -1.4426950408889634f)); }
;     __device__ __forceinline__ void operator()(const f32x4 (&acc)[2][2][4][2], const Unit& u, int wr, int wc, int fr, int fq) const {
;     ...
;             for (int m = 0; m < 4; ++m) { const int row = row0 + ai * HALF + m * 16; const float rs = rsv[ai][m];
;                 f32x4 g0 = acc[ai][0][m][0] * rs, g1 = acc[ai][0][m][1] * rs; const f32x4 t0 = acc[ai][1][m][0] * rs, t1 = acc[ai][1][m][1] * rs;
;                 if (silu) {
; #pragma unroll
;                     for (int j = 0; j < 4; ++j) { g0[j] = silu_f(g0[j]); g1[j] = silu_f(g1[j]); } }
;                 g0 = g0 * t0; g1 = g1 * t1;
;                 u32x4 w; w.x = cvt_pk_bf16(g0[0], g0[1]); w.y = cvt_pk_bf16(g0[2], g0[3]); w.z = cvt_pk_bf16(g1[0], g1[1]); w.w = cvt_pk_bf16(g1[2], g1[3]);
;                 *(u32x4*)(O + (size_t)row * ldc + col0 + (size_t)(row >> 12) * adj) = w; }
	v_mul_f32_e32 v170, 0xbfb8aa3b, v242
	v_mul_f32_e32 v172, v242, v242
	v_pk_mul_f32 v[146:147], v[102:103], v[170:171] op_sel_hi:[1,0]
	v_pk_mul_f32 v[148:149], v[104:105], v[170:171] op_sel_hi:[1,0]
	v_pk_mul_f32 v[150:151], v[98:99], v[170:171] op_sel_hi:[1,0]
	v_pk_mul_f32 v[152:153], v[100:101], v[170:171] op_sel_hi:[1,0]
	v_pk_mul_f32 v[122:123], v[122:123], v[154:155]
	v_pk_mul_f32 v[124:125], v[124:125], v[156:157]
	v_pk_mul_f32 v[118:119], v[118:119], v[158:159]
	v_pk_mul_f32 v[120:121], v[120:121], v[160:161]
	v_cvt_pk_bf16_f32 v166, v122, v123
	v_cvt_pk_bf16_f32 v167, v124, v125
	v_cvt_pk_bf16_f32 v168, v118, v119
	v_cvt_pk_bf16_f32 v169, v120, v121
	global_store_dwordx4 v190, v[166:169], s[10:11]
	v_add_u32_e32 v190, s30, v190
	v_exp_f32_e32 v146, v146
	v_exp_f32_e32 v147, v147
	v_exp_f32_e32 v148, v148
	v_exp_f32_e32 v149, v149
	v_exp_f32_e32 v150, v150
	v_exp_f32_e32 v151, v151
	v_exp_f32_e32 v152, v152
	v_exp_f32_e32 v153, v153
	v_pk_mul_f32 v[102:103], v[102:103], v[90:91]
	v_pk_mul_f32 v[104:105], v[104:105], v[92:93]
	v_pk_mul_f32 v[98:99], v[98:99], v[86:87]
	v_pk_mul_f32 v[100:101], v[100:101], v[88:89]
	v_pk_add_f32 v[146:147], v[146:147], v[188:189]
	v_pk_add_f32 v[148:149], v[148:149], v[188:189]
	v_pk_add_f32 v[150:151], v[150:151], v[188:189]
	v_pk_add_f32 v[152:153], v[152:153], v[188:189]
	v_pk_mul_f32 v[102:103], v[102:103], v[172:173] op_sel_hi:[1,0]
	v_pk_mul_f32 v[104:105], v[104:105], v[172:173] op_sel_hi:[1,0]
	v_pk_mul_f32 v[98:99], v[98:99], v[172:173] op_sel_hi:[1,0]
	v_pk_mul_f32 v[100:101], v[100:101], v[172:173] op_sel_hi:[1,0]
	v_rcp_f32_e32 v146, v146
	v_rcp_f32_e32 v147, v147
	v_rcp_f32_e32 v148, v148
	v_rcp_f32_e32 v149, v149
	v_rcp_f32_e32 v150, v150
	v_rcp_f32_e32 v151, v151
	v_rcp_f32_e32 v152, v152
	v_rcp_f32_e32 v153, v153
	v_mul_f32_e32 v174, 0xbfb8aa3b, v243
	v_mul_f32_e32 v176, v243, v243
	v_pk_mul_f32 v[154:155], v[82:83], v[174:175] op_sel_hi:[1,0]
	v_pk_mul_f32 v[156:157], v[84:85], v[174:175] op_sel_hi:[1,0]
	v_pk_mul_f32 v[158:159], v[78:79], v[174:175] op_sel_hi:[1,0]
	v_pk_mul_f32 v[160:161], v[80:81], v[174:175] op_sel_hi:[1,0]
	v_pk_mul_f32 v[102:103], v[102:103], v[146:147]
	v_pk_mul_f32 v[104:105], v[104:105], v[148:149]
	v_pk_mul_f32 v[98:99], v[98:99], v[150:151]
	v_pk_mul_f32 v[100:101], v[100:101], v[152:153]
	v_cvt_pk_bf16_f32 v162, v102, v103
	v_cvt_pk_bf16_f32 v163, v104, v105
	v_cvt_pk_bf16_f32 v164, v98, v99
	v_cvt_pk_bf16_f32 v165, v100, v101
	global_store_dwordx4 v190, v[162:165], s[10:11]
	v_add_u32_e32 v190, s30, v190
	v_exp_f32_e32 v154, v154
	v_exp_f32_e32 v155, v155
	v_exp_f32_e32 v156, v156
	v_exp_f32_e32 v157, v157
	v_exp_f32_e32 v158, v158
	v_exp_f32_e32 v159, v159
	v_exp_f32_e32 v160, v160
	v_exp_f32_e32 v161, v161
	v_pk_mul_f32 v[82:83], v[82:83], v[70:71]
	v_pk_mul_f32 v[84:85], v[84:85], v[72:73]
	v_pk_mul_f32 v[78:79], v[78:79], v[66:67]
	v_pk_mul_f32 v[80:81], v[80:81], v[68:69]
	v_pk_add_f32 v[154:155], v[154:155], v[188:189]
	v_pk_add_f32 v[156:157], v[156:157], v[188:189]
	v_pk_add_f32 v[158:159], v[158:159], v[188:189]
	v_pk_add_f32 v[160:161], v[160:161], v[188:189]
	v_pk_mul_f32 v[82:83], v[82:83], v[176:177] op_sel_hi:[1,0]
	v_pk_mul_f32 v[84:85], v[84:85], v[176:177] op_sel_hi:[1,0]
	v_pk_mul_f32 v[78:79], v[78:79], v[176:177] op_sel_hi:[1,0]
	v_pk_mul_f32 v[80:81], v[80:81], v[176:177] op_sel_hi:[1,0]
	v_rcp_f32_e32 v154, v154
	v_rcp_f32_e32 v155, v155
	v_rcp_f32_e32 v156, v156
	v_rcp_f32_e32 v157, v157
	v_rcp_f32_e32 v158, v158
	v_rcp_f32_e32 v159, v159
	v_rcp_f32_e32 v160, v160
	v_rcp_f32_e32 v161, v161
	v_mul_f32_e32 v170, 0xbfb8aa3b, v244
	v_mul_f32_e32 v172, v244, v244
	v_pk_mul_f32 v[146:147], v[62:63], v[170:171] op_sel_hi:[1,0]
	v_pk_mul_f32 v[148:149], v[64:65], v[170:171] op_sel_hi:[1,0]
	v_pk_mul_f32 v[150:151], v[58:59], v[170:171] op_sel_hi:[1,0]
	v_pk_mul_f32 v[152:153], v[60:61], v[170:171] op_sel_hi:[1,0]
	v_pk_mul_f32 v[82:83], v[82:83], v[154:155]
	v_pk_mul_f32 v[84:85], v[84:85], v[156:157]
	v_pk_mul_f32 v[78:79], v[78:79], v[158:159]
	v_pk_mul_f32 v[80:81], v[80:81], v[160:161]
	v_cvt_pk_bf16_f32 v166, v82, v83
	v_cvt_pk_bf16_f32 v167, v84, v85
	v_cvt_pk_bf16_f32 v168, v78, v79
	v_cvt_pk_bf16_f32 v169, v80, v81
	global_store_dwordx4 v190, v[166:169], s[10:11]
	v_add_u32_e32 v190, s31, v190
	v_exp_f32_e32 v146, v146
	v_exp_f32_e32 v147, v147
	v_exp_f32_e32 v148, v148
	v_exp_f32_e32 v149, v149
	v_exp_f32_e32 v150, v150
	v_exp_f32_e32 v151, v151
	v_exp_f32_e32 v152, v152
	v_exp_f32_e32 v153, v153
	v_pk_mul_f32 v[62:63], v[62:63], v[54:55]
	v_pk_mul_f32 v[64:65], v[64:65], v[56:57]
	v_pk_mul_f32 v[58:59], v[58:59], v[50:51]
	v_pk_mul_f32 v[60:61], v[60:61], v[52:53]
	v_pk_add_f32 v[146:147], v[146:147], v[188:189]
	v_pk_add_f32 v[148:149], v[148:149], v[188:189]
	v_pk_add_f32 v[150:151], v[150:151], v[188:189]
	v_pk_add_f32 v[152:153], v[152:153], v[188:189]
	v_pk_mul_f32 v[62:63], v[62:63], v[172:173] op_sel_hi:[1,0]
	v_pk_mul_f32 v[64:65], v[64:65], v[172:173] op_sel_hi:[1,0]
	v_pk_mul_f32 v[58:59], v[58:59], v[172:173] op_sel_hi:[1,0]
	v_pk_mul_f32 v[60:61], v[60:61], v[172:173] op_sel_hi:[1,0]
	v_rcp_f32_e32 v146, v146
	v_rcp_f32_e32 v147, v147
	v_rcp_f32_e32 v148, v148
	v_rcp_f32_e32 v149, v149
	v_rcp_f32_e32 v150, v150
	v_rcp_f32_e32 v151, v151
	v_rcp_f32_e32 v152, v152
	v_rcp_f32_e32 v153, v153
	v_mul_f32_e32 v174, 0xbfb8aa3b, v245
	v_mul_f32_e32 v176, v245, v245
	v_pk_mul_f32 v[154:155], v[46:47], v[174:175] op_sel_hi:[1,0]
	v_pk_mul_f32 v[156:157], v[48:49], v[174:175] op_sel_hi:[1,0]
; __device__ __forceinline__ unsigned cvt_pk_bf16(float lo, float hi) { unsigned r; asm volatile("v_cvt_pk_bf16_f32 %0, %1, %2" : "=v"(r) : "v"(lo), "v"(hi)); return r; }
; __device__ __forceinline__ float silu_f(float g) { return g * __builtin_amdgcn_rcpf(1.0f + __builtin_amdgcn_exp2f(g * -1.4426950408889634f)); }
;     __device__ __forceinline__ void operator()(const f32x4 (&acc)[2][2][4][2], const Unit& u, int wr, int wc, int fr, int fq) const {
;     ...
;             for (int m = 0; m < 4; ++m) { const int row = row0 + ai * HALF + m * 16; const float rs = rsv[ai][m];
;                 f32x4 g0 = acc[ai][0][m][0] * rs, g1 = acc[ai][0][m][1] * rs; const f32x4 t0 = acc[ai][1][m][0] * rs, t1 = acc[ai][1][m][1] * rs;
;                 if (silu) {
; #pragma unroll
;                     for (int j = 0; j < 4; ++j) { g0[j] = silu_f(g0[j]); g1[j] = silu_f(g1[j]); } }
;                 g0 = g0 * t0; g1 = g1 * t1;
;                 u32x4 w; w.x = cvt_pk_bf16(g0[0], g0[1]); w.y = cvt_pk_bf16(g0[2], g0[3]); w.z = cvt_pk_bf16(g1[0], g1[1]); w.w = cvt_pk_bf16(g1[2], g1[3]);
;                 *(u32x4*)(O + (size_t)row * ldc + col0 + (size_t)(row >> 12) * adj) = w; }
; template <class Epi, bool ALIGN_EPI>
; __device__ __forceinline__ void gemm_phase(LAS unsigned char* lds, const Gemm g, const StaticOrder& S, const Epi& E) {
;     ...
;         if (!has_next) break;
	v_pk_mul_f32 v[158:159], v[42:43], v[174:175] op_sel_hi:[1,0]
	v_pk_mul_f32 v[160:161], v[44:45], v[174:175] op_sel_hi:[1,0]
	v_pk_mul_f32 v[62:63], v[62:63], v[146:147]
	v_pk_mul_f32 v[64:65], v[64:65], v[148:149]
	v_pk_mul_f32 v[58:59], v[58:59], v[150:151]
	v_pk_mul_f32 v[60:61], v[60:61], v[152:153]
	v_cvt_pk_bf16_f32 v162, v62, v63
	v_cvt_pk_bf16_f32 v163, v64, v65
	v_cvt_pk_bf16_f32 v164, v58, v59
	v_cvt_pk_bf16_f32 v165, v60, v61
	global_store_dwordx4 v190, v[162:165], s[10:11]
	v_add_u32_e32 v190, s30, v190
	v_exp_f32_e32 v154, v154
	v_exp_f32_e32 v155, v155
	v_exp_f32_e32 v156, v156
	v_exp_f32_e32 v157, v157
	v_exp_f32_e32 v158, v158
	v_exp_f32_e32 v159, v159
	v_exp_f32_e32 v160, v160
	v_exp_f32_e32 v161, v161
	v_pk_mul_f32 v[46:47], v[46:47], v[38:39]
	v_pk_mul_f32 v[48:49], v[48:49], v[40:41]
	v_pk_mul_f32 v[42:43], v[42:43], v[34:35]
	v_pk_mul_f32 v[44:45], v[44:45], v[36:37]
	v_pk_add_f32 v[154:155], v[154:155], v[188:189]
	v_pk_add_f32 v[156:157], v[156:157], v[188:189]
	v_pk_add_f32 v[158:159], v[158:159], v[188:189]
	v_pk_add_f32 v[160:161], v[160:161], v[188:189]
	v_pk_mul_f32 v[46:47], v[46:47], v[176:177] op_sel_hi:[1,0]
	v_pk_mul_f32 v[48:49], v[48:49], v[176:177] op_sel_hi:[1,0]
	v_pk_mul_f32 v[42:43], v[42:43], v[176:177] op_sel_hi:[1,0]
	v_pk_mul_f32 v[44:45], v[44:45], v[176:177] op_sel_hi:[1,0]
	v_rcp_f32_e32 v154, v154
	v_rcp_f32_e32 v155, v155
	v_rcp_f32_e32 v156, v156
	v_rcp_f32_e32 v157, v157
	v_rcp_f32_e32 v158, v158
	v_rcp_f32_e32 v159, v159
	v_rcp_f32_e32 v160, v160
	v_rcp_f32_e32 v161, v161
	v_mul_f32_e32 v170, 0xbfb8aa3b, v246
	v_mul_f32_e32 v172, v246, v246
	v_pk_mul_f32 v[146:147], v[30:31], v[170:171] op_sel_hi:[1,0]
	v_pk_mul_f32 v[148:149], v[32:33], v[170:171] op_sel_hi:[1,0]
	v_pk_mul_f32 v[150:151], v[26:27], v[170:171] op_sel_hi:[1,0]
	v_pk_mul_f32 v[152:153], v[28:29], v[170:171] op_sel_hi:[1,0]
	v_pk_mul_f32 v[46:47], v[46:47], v[154:155]
	v_pk_mul_f32 v[48:49], v[48:49], v[156:157]
	v_pk_mul_f32 v[42:43], v[42:43], v[158:159]
	v_pk_mul_f32 v[44:45], v[44:45], v[160:161]
	v_cvt_pk_bf16_f32 v166, v46, v47
	v_cvt_pk_bf16_f32 v167, v48, v49
	v_cvt_pk_bf16_f32 v168, v42, v43
	v_cvt_pk_bf16_f32 v169, v44, v45
	global_store_dwordx4 v190, v[166:169], s[10:11]
	v_add_u32_e32 v190, s30, v190
	v_exp_f32_e32 v146, v146
	v_exp_f32_e32 v147, v147
	v_exp_f32_e32 v148, v148
	v_exp_f32_e32 v149, v149
	v_exp_f32_e32 v150, v150
	v_exp_f32_e32 v151, v151
	v_exp_f32_e32 v152, v152
	v_exp_f32_e32 v153, v153
	v_pk_mul_f32 v[30:31], v[30:31], v[22:23]
	v_pk_mul_f32 v[32:33], v[32:33], v[24:25]
	v_pk_mul_f32 v[26:27], v[26:27], v[18:19]
	v_pk_mul_f32 v[28:29], v[28:29], v[20:21]
	v_pk_add_f32 v[146:147], v[146:147], v[188:189]
	v_pk_add_f32 v[148:149], v[148:149], v[188:189]
	v_pk_add_f32 v[150:151], v[150:151], v[188:189]
	v_pk_add_f32 v[152:153], v[152:153], v[188:189]
	v_pk_mul_f32 v[30:31], v[30:31], v[172:173] op_sel_hi:[1,0]
	v_pk_mul_f32 v[32:33], v[32:33], v[172:173] op_sel_hi:[1,0]
	v_pk_mul_f32 v[26:27], v[26:27], v[172:173] op_sel_hi:[1,0]
	v_pk_mul_f32 v[28:29], v[28:29], v[172:173] op_sel_hi:[1,0]
	v_rcp_f32_e32 v146, v146
	v_rcp_f32_e32 v147, v147
	v_rcp_f32_e32 v148, v148
	v_rcp_f32_e32 v149, v149
	v_rcp_f32_e32 v150, v150
	v_rcp_f32_e32 v151, v151
	v_rcp_f32_e32 v152, v152
	v_rcp_f32_e32 v153, v153
	v_mul_f32_e32 v174, 0xbfb8aa3b, v247
	v_mul_f32_e32 v176, v247, v247
	v_pk_mul_f32 v[154:155], v[14:15], v[174:175] op_sel_hi:[1,0]
	v_pk_mul_f32 v[156:157], v[16:17], v[174:175] op_sel_hi:[1,0]
	v_pk_mul_f32 v[158:159], v[10:11], v[174:175] op_sel_hi:[1,0]
	v_pk_mul_f32 v[160:161], v[12:13], v[174:175] op_sel_hi:[1,0]
	v_pk_mul_f32 v[30:31], v[30:31], v[146:147]
	v_pk_mul_f32 v[32:33], v[32:33], v[148:149]
	v_pk_mul_f32 v[26:27], v[26:27], v[150:151]
	v_pk_mul_f32 v[28:29], v[28:29], v[152:153]
	v_cvt_pk_bf16_f32 v162, v30, v31
	v_cvt_pk_bf16_f32 v163, v32, v33
	v_cvt_pk_bf16_f32 v164, v26, v27
	v_cvt_pk_bf16_f32 v165, v28, v29
	global_store_dwordx4 v190, v[162:165], s[10:11]
	v_add_u32_e32 v190, s30, v190
	v_exp_f32_e32 v154, v154
	v_exp_f32_e32 v155, v155
	v_exp_f32_e32 v156, v156
	v_exp_f32_e32 v157, v157
	v_exp_f32_e32 v158, v158
	v_exp_f32_e32 v159, v159
	v_exp_f32_e32 v160, v160
	v_exp_f32_e32 v161, v161
	v_pk_mul_f32 v[14:15], v[14:15], v[6:7]
	v_pk_mul_f32 v[16:17], v[16:17], v[8:9]
	v_pk_mul_f32 v[10:11], v[10:11], v[2:3]
	v_pk_mul_f32 v[12:13], v[12:13], v[4:5]
	v_pk_add_f32 v[154:155], v[154:155], v[188:189]
	v_pk_add_f32 v[156:157], v[156:157], v[188:189]
	v_pk_add_f32 v[158:159], v[158:159], v[188:189]
	v_pk_add_f32 v[160:161], v[160:161], v[188:189]
	v_pk_mul_f32 v[14:15], v[14:15], v[176:177] op_sel_hi:[1,0]
	v_pk_mul_f32 v[16:17], v[16:17], v[176:177] op_sel_hi:[1,0]
	v_pk_mul_f32 v[10:11], v[10:11], v[176:177] op_sel_hi:[1,0]
	v_pk_mul_f32 v[12:13], v[12:13], v[176:177] op_sel_hi:[1,0]
	v_rcp_f32_e32 v154, v154
	v_rcp_f32_e32 v155, v155
	v_rcp_f32_e32 v156, v156
	v_rcp_f32_e32 v157, v157
	v_rcp_f32_e32 v158, v158
	v_rcp_f32_e32 v159, v159
	v_rcp_f32_e32 v160, v160
	v_rcp_f32_e32 v161, v161
	v_pk_mul_f32 v[14:15], v[14:15], v[154:155]
	v_pk_mul_f32 v[16:17], v[16:17], v[156:157]
	v_pk_mul_f32 v[10:11], v[10:11], v[158:159]
	v_pk_mul_f32 v[12:13], v[12:13], v[160:161]
	v_cvt_pk_bf16_f32 v166, v14, v15
	v_cvt_pk_bf16_f32 v167, v16, v17
	v_cvt_pk_bf16_f32 v168, v10, v11
	v_cvt_pk_bf16_f32 v169, v12, v13
	global_store_dwordx4 v190, v[166:169], s[10:11]
	s_andn2_b64 vcc, exec, s[8:9]
	s_mov_b64 s[4:5], -1
	s_branch .Lep_join
